# grid barrier: wave 1 issues its cache invalidate before the workgroup barrier (after its own stores are acknowledged) so the invalidate and the code warming behind it finish sooner
# speedup vs baseline: 1.0020x; 1.0020x over previous
; __device__ __forceinline__ void xcd_barrier(const XcdBarrier& b) {
;     asm volatile("s_waitcnt vmcnt(0)" ::: "memory");
;     __syncthreads();
;     if (threadIdx.x == 0) {
.Linit_done:
	s_or_b64 exec, exec, s[4:5]
	s_waitcnt vmcnt(0)
	s_waitcnt lgkmcnt(0)
	v_readfirstlane_b32 s2, v152
	s_cmp_lg_u32 s2, 64
	s_cbranch_scc1 .Lpreinv_0
	buffer_inv sc1
.Lpreinv_0:
	s_barrier
	v_readfirstlane_b32 s2, v152
	s_cmp_lg_u32 s2, 64
	s_cbranch_scc1 .Leinv_skip_0
	s_waitcnt vmcnt(0)
	s_getpc_b64 s[2:3]

; __device__ __forceinline__ void xcd_barrier(const XcdBarrier& b) {
;     asm volatile("s_waitcnt vmcnt(0)" ::: "memory");
;     __syncthreads();
;     if (threadIdx.x == 0) {
.LBB0_296:
	s_waitcnt vmcnt(0)
	s_waitcnt vmcnt(0)
	v_readfirstlane_b32 s2, v152
	s_cmp_lg_u32 s2, 64
	s_cbranch_scc1 .Lpreinv_1
	buffer_inv sc1

; __device__ __forceinline__ void xcd_barrier(const XcdBarrier& b) {
;     asm volatile("s_waitcnt vmcnt(0)" ::: "memory");
;     __syncthreads();
;     if (threadIdx.x == 0) {
.LBB0_395:
	s_waitcnt vmcnt(0)
	s_waitcnt lgkmcnt(0)
	v_readfirstlane_b32 s2, v152
	s_cmp_lg_u32 s2, 64
	s_cbranch_scc1 .Lpreinv_2
	buffer_inv sc1

; __device__ __forceinline__ void xcd_barrier(const XcdBarrier& b) {
;     asm volatile("s_waitcnt vmcnt(0)" ::: "memory");
;     __syncthreads();
;     if (threadIdx.x == 0) {
.LBB0_977:
	s_waitcnt vmcnt(0)
	v_readfirstlane_b32 s2, v152
	s_cmp_lg_u32 s2, 64
	s_cbranch_scc1 .Lpreinv_4
	buffer_inv sc1
